# speedup vs baseline: 1.0075x; 1.0075x over previous
.LBB0_60:
	s_mul_i32 s83, s83, s95
	s_sub_i32 s72, s94, s83
	s_lshl_b32 s83, s72, 6
	v_add_u32_e32 v2, s89, v1
	v_ashrrev_i32_e32 v1, 4, v4
	v_add_u32_e32 v10, s83, v1
	v_ashrrev_i32_e32 v6, 31, v10
	v_ashrrev_i32_e32 v3, 31, v2
	v_mul_lo_u32 v8, s78, v6
	v_mul_lo_u32 v9, s79, v10
	v_mad_u64_u32 v[6:7], s[72:73], s78, v10, 0
	v_add_u32_e32 v10, 32, v10
	v_lshl_add_u64 v[2:3], v[2:3], 2, s[76:77]
	v_add3_u32 v7, v7, v8, v9
	v_ashrrev_i32_e32 v11, 31, v10
	v_lshl_add_u64 v[6:7], v[6:7], 2, v[2:3]
	v_mul_lo_u32 v12, s78, v11
	v_mul_lo_u32 v13, s79, v10
	v_mad_u64_u32 v[10:11], s[72:73], s78, v10, 0
	global_load_dwordx4 v[6:9], v[6:7], off nt
	v_add3_u32 v11, v11, v12, v13
	v_lshl_add_u64 v[2:3], v[10:11], 2, v[2:3]
	global_load_dwordx4 v[14:17], v[2:3], off nt
	v_lshlrev_b32_e32 v12, 3, v4
	v_mul_lo_u32 v1, v1, s86
	v_and_b32_e32 v18, 56, v12
	v_ashrrev_i32_e32 v13, 3, v4
	v_lshl_add_u32 v0, v0, 2, v1
	v_mul_u32_u24_e32 v1, 0x104, v18
	v_lshl_add_u32 v10, v13, 2, v1
	v_add_u32_e32 v2, 0x2080, v0
	v_add_u32_e32 v3, 0x2088, v0
	v_add_u32_e32 v11, 0x400, v10
	s_cmp_eq_u64 s[74:75], 0
	s_waitcnt vmcnt(1)
	ds_write2_b32 v0, v6, v7 offset1:1
	ds_write2_b32 v0, v8, v9 offset0:2 offset1:3
	s_waitcnt vmcnt(0)
	ds_write2_b32 v2, v14, v15 offset1:1
	ds_write2_b32 v3, v16, v17 offset1:1
	s_cbranch_scc1 .Lkg_skip
	v_or_b32_e32 v244, s83, v18
	v_ashrrev_i32_e32 v245, 31, v244
	v_lshl_add_u64 v[246:247], v[244:245], 2, s[74:75]
	global_load_dwordx4 v[248:251], v[246:247], off
	global_load_dwordx4 v[252:255], v[246:247], off offset:16
.Lkg_skip:
	s_waitcnt lgkmcnt(0)
	s_barrier
	ds_read2_b32 v[0:1], v10 offset1:65
	ds_read2_b32 v[8:9], v10 offset0:130 offset1:195
	ds_read2_b32 v[2:3], v11 offset0:4 offset1:69
	ds_read2_b32 v[10:11], v11 offset0:134 offset1:199
	v_or_b32_e32 v6, s83, v18
	s_cbranch_scc1 .LBB0_62
	s_waitcnt vmcnt(1) lgkmcnt(3)
	v_pk_mul_f32 v[0:1], v[0:1], v[248:249]
	s_waitcnt lgkmcnt(2)
	v_pk_mul_f32 v[8:9], v[8:9], v[250:251]
	s_waitcnt vmcnt(0) lgkmcnt(1)
	v_pk_mul_f32 v[2:3], v[2:3], v[252:253]
	s_waitcnt lgkmcnt(0)
	v_pk_mul_f32 v[10:11], v[10:11], v[254:255]
